# GEMM K-loop headers aligned to 256 bytes
# baseline (speedup 1.0000x reference)
.LBB0_99:
	s_ashr_i32 s43, s42, 31
	s_lshl_b64 s[20:21], s[42:43], 21
	v_cmp_lt_i64_e32 vcc, s[44:45], v[186:187]
	s_add_u32 s44, s70, s20
	s_addc_u32 s45, s71, s21
	s_and_b64 s[20:21], vcc, exec
	s_cselect_b32 s43, s45, s49
	s_cselect_b32 s24, s44, s48
	s_ashr_i32 s1, s0, 31
	s_lshl_b64 s[20:21], s[0:1], 21
	v_readlane_b32 s46, v254, 27
	v_readlane_b32 s47, v254, 28
	s_add_u32 s46, s46, s20
	s_addc_u32 s47, s47, s21
	s_and_b64 s[20:21], vcc, exec
	s_cselect_b32 s1, s47, s29
	s_cselect_b32 s25, s46, s28
	s_add_u32 s48, s48, 0x100080
	s_addc_u32 s49, s49, 0
	s_add_u32 vcc_lo, s28, 0x100
	v_mov_b32_e32 v0, 0
	s_addc_u32 vcc_hi, s29, 0
	s_mov_b32 s20, -2
	v_mov_b32_e32 v1, v0
	v_mov_b64_e32 v[2:3], 0
	v_mov_b64_e32 v[4:5], 0
	v_mov_b64_e32 v[6:7], 0
	v_mov_b64_e32 v[16:17], 0
	v_mov_b64_e32 v[18:19], 0
	v_mov_b64_e32 v[20:21], 0
	v_mov_b64_e32 v[22:23], 0
	v_mov_b64_e32 v[32:33], 0
	v_mov_b64_e32 v[34:35], 0
	v_mov_b64_e32 v[36:37], 0
	v_mov_b64_e32 v[38:39], 0
	v_mov_b64_e32 v[48:49], 0
	v_mov_b64_e32 v[50:51], 0
	v_mov_b64_e32 v[52:53], 0
	v_mov_b64_e32 v[54:55], 0
	v_mov_b64_e32 v[8:9], 0
	v_mov_b64_e32 v[10:11], 0
	v_mov_b64_e32 v[12:13], 0
	v_mov_b64_e32 v[14:15], 0
	v_mov_b64_e32 v[24:25], 0
	v_mov_b64_e32 v[26:27], 0
	v_mov_b64_e32 v[28:29], 0
	v_mov_b64_e32 v[30:31], 0
	v_mov_b64_e32 v[40:41], 0
	v_mov_b64_e32 v[42:43], 0
	v_mov_b64_e32 v[44:45], 0
	v_mov_b64_e32 v[46:47], 0
	v_mov_b64_e32 v[56:57], 0
	v_mov_b64_e32 v[58:59], 0
	v_mov_b64_e32 v[60:61], 0
	v_mov_b64_e32 v[62:63], 0
	v_mov_b64_e32 v[64:65], 0
	v_mov_b64_e32 v[66:67], 0
	v_mov_b64_e32 v[68:69], 0
	v_mov_b64_e32 v[70:71], 0
	v_mov_b64_e32 v[80:81], 0
	v_mov_b64_e32 v[82:83], 0
	v_mov_b64_e32 v[84:85], 0
	v_mov_b64_e32 v[86:87], 0
	v_mov_b64_e32 v[96:97], 0
	v_mov_b64_e32 v[98:99], 0
	v_mov_b64_e32 v[100:101], 0
	v_mov_b64_e32 v[102:103], 0
	v_mov_b64_e32 v[136:137], 0
	v_mov_b64_e32 v[138:139], 0
	v_mov_b64_e32 v[140:141], 0
	v_mov_b64_e32 v[142:143], 0
	v_mov_b64_e32 v[72:73], 0
	v_mov_b64_e32 v[74:75], 0
	v_mov_b64_e32 v[76:77], 0
	v_mov_b64_e32 v[78:79], 0
	v_mov_b64_e32 v[88:89], 0
	v_mov_b64_e32 v[90:91], 0
	v_mov_b64_e32 v[92:93], 0
	v_mov_b64_e32 v[94:95], 0
	v_mov_b64_e32 v[104:105], 0
	v_mov_b64_e32 v[106:107], 0
	v_mov_b64_e32 v[108:109], 0
	v_mov_b64_e32 v[110:111], 0
	v_mov_b64_e32 v[144:145], 0
	v_mov_b64_e32 v[146:147], 0
	v_mov_b64_e32 v[148:149], 0
	v_mov_b64_e32 v[150:151], 0
	.p2align	8

.LBB0_146:
	s_ashr_i32 s43, s42, 31
	s_lshl_b64 s[20:21], s[42:43], 19
	v_cmp_lt_i64_e32 vcc, s[44:45], v[190:191]
	s_add_u32 s44, s68, s20
	s_addc_u32 s45, s69, s21
	s_and_b64 s[20:21], vcc, exec
	s_cselect_b32 s43, s45, s1
	s_cselect_b32 s24, s44, s0
	s_ashr_i32 s41, s40, 31
	s_lshl_b64 s[20:21], s[40:41], 19
	v_readlane_b32 s46, v253, 62
	v_readlane_b32 s47, v253, 63
	s_add_u32 s46, s46, s20
	s_addc_u32 s47, s47, s21
	s_and_b64 s[20:21], vcc, exec
	s_cselect_b32 s25, s47, s29
	s_cselect_b32 s41, s46, s28
	s_add_u32 s0, s0, 0x40080
	s_addc_u32 s1, s1, 0
	s_add_u32 vcc_lo, s28, 0x100
	v_mov_b32_e32 v0, 0
	s_addc_u32 vcc_hi, s29, 0
	s_mov_b32 s20, -2
	v_mov_b32_e32 v1, v0
	v_mov_b64_e32 v[2:3], 0
	v_mov_b64_e32 v[4:5], 0
	v_mov_b64_e32 v[6:7], 0
	v_mov_b64_e32 v[16:17], 0
	v_mov_b64_e32 v[18:19], 0
	v_mov_b64_e32 v[20:21], 0
	v_mov_b64_e32 v[22:23], 0
	v_mov_b64_e32 v[32:33], 0
	v_mov_b64_e32 v[34:35], 0
	v_mov_b64_e32 v[36:37], 0
	v_mov_b64_e32 v[38:39], 0
	v_mov_b64_e32 v[48:49], 0
	v_mov_b64_e32 v[50:51], 0
	v_mov_b64_e32 v[52:53], 0
	v_mov_b64_e32 v[54:55], 0
	v_mov_b64_e32 v[8:9], 0
	v_mov_b64_e32 v[10:11], 0
	v_mov_b64_e32 v[12:13], 0
	v_mov_b64_e32 v[14:15], 0
	v_mov_b64_e32 v[24:25], 0
	v_mov_b64_e32 v[26:27], 0
	v_mov_b64_e32 v[28:29], 0
	v_mov_b64_e32 v[30:31], 0
	v_mov_b64_e32 v[40:41], 0
	v_mov_b64_e32 v[42:43], 0
	v_mov_b64_e32 v[44:45], 0
	v_mov_b64_e32 v[46:47], 0
	v_mov_b64_e32 v[56:57], 0
	v_mov_b64_e32 v[58:59], 0
	v_mov_b64_e32 v[60:61], 0
	v_mov_b64_e32 v[62:63], 0
	v_mov_b64_e32 v[64:65], 0
	v_mov_b64_e32 v[66:67], 0
	v_mov_b64_e32 v[68:69], 0
	v_mov_b64_e32 v[70:71], 0
	v_mov_b64_e32 v[80:81], 0
	v_mov_b64_e32 v[82:83], 0
	v_mov_b64_e32 v[84:85], 0
	v_mov_b64_e32 v[86:87], 0
	v_mov_b64_e32 v[96:97], 0
	v_mov_b64_e32 v[98:99], 0
	v_mov_b64_e32 v[100:101], 0
	v_mov_b64_e32 v[102:103], 0
	v_mov_b64_e32 v[112:113], 0
	v_mov_b64_e32 v[114:115], 0
	v_mov_b64_e32 v[116:117], 0
	v_mov_b64_e32 v[118:119], 0
	v_mov_b64_e32 v[72:73], 0
	v_mov_b64_e32 v[74:75], 0
	v_mov_b64_e32 v[76:77], 0
	v_mov_b64_e32 v[78:79], 0
	v_mov_b64_e32 v[88:89], 0
	v_mov_b64_e32 v[90:91], 0
	v_mov_b64_e32 v[92:93], 0
	v_mov_b64_e32 v[94:95], 0
	v_mov_b64_e32 v[104:105], 0
	v_mov_b64_e32 v[106:107], 0
	v_mov_b64_e32 v[108:109], 0
	v_mov_b64_e32 v[110:111], 0
	v_mov_b64_e32 v[120:121], 0
	v_mov_b64_e32 v[122:123], 0
	v_mov_b64_e32 v[124:125], 0
	v_mov_b64_e32 v[126:127], 0
	.p2align	8

.LBB0_169:
	s_ashr_i32 s43, s42, 31
	s_lshl_b64 s[20:21], s[42:43], 19
	v_readlane_b32 s24, v254, 43
	v_cmp_lt_i64_e32 vcc, s[44:45], v[186:187]
	v_readlane_b32 s25, v254, 44
	s_add_u32 s44, s24, s20
	s_addc_u32 s45, s25, s21
	s_and_b64 s[20:21], vcc, exec
	s_cselect_b32 s43, s45, s49
	s_cselect_b32 s24, s44, s48
	s_ashr_i32 s1, s0, 31
	s_lshl_b64 s[20:21], s[0:1], 19
	v_readlane_b32 s46, v254, 41
	v_readlane_b32 s47, v254, 42
	s_add_u32 s46, s46, s20
	s_addc_u32 s47, s47, s21
	s_and_b64 s[20:21], vcc, exec
	s_cselect_b32 s1, s47, s29
	s_cselect_b32 s25, s46, s28
	s_add_u32 s48, s48, 0x40080
	s_addc_u32 s49, s49, 0
	s_add_u32 vcc_lo, s28, 0x100
	v_mov_b32_e32 v0, 0
	s_mov_b64 s[92:93], s[74:75]
	s_addc_u32 vcc_hi, s29, 0
	s_mov_b32 s57, -2
	v_mov_b32_e32 v1, v0
	v_mov_b64_e32 v[2:3], 0
	v_mov_b64_e32 v[4:5], 0
	v_mov_b64_e32 v[6:7], 0
	v_mov_b64_e32 v[16:17], 0
	v_mov_b64_e32 v[18:19], 0
	v_mov_b64_e32 v[20:21], 0
	v_mov_b64_e32 v[22:23], 0
	v_mov_b64_e32 v[32:33], 0
	v_mov_b64_e32 v[34:35], 0
	v_mov_b64_e32 v[36:37], 0
	v_mov_b64_e32 v[38:39], 0
	v_mov_b64_e32 v[48:49], 0
	v_mov_b64_e32 v[50:51], 0
	v_mov_b64_e32 v[52:53], 0
	v_mov_b64_e32 v[54:55], 0
	v_mov_b64_e32 v[8:9], 0
	v_mov_b64_e32 v[10:11], 0
	v_mov_b64_e32 v[12:13], 0
	v_mov_b64_e32 v[14:15], 0
	v_mov_b64_e32 v[24:25], 0
	v_mov_b64_e32 v[26:27], 0
	v_mov_b64_e32 v[28:29], 0
	v_mov_b64_e32 v[30:31], 0
	v_mov_b64_e32 v[40:41], 0
	v_mov_b64_e32 v[42:43], 0
	v_mov_b64_e32 v[44:45], 0
	v_mov_b64_e32 v[46:47], 0
	v_mov_b64_e32 v[56:57], 0
	v_mov_b64_e32 v[58:59], 0
	v_mov_b64_e32 v[60:61], 0
	v_mov_b64_e32 v[62:63], 0
	v_mov_b64_e32 v[64:65], 0
	v_mov_b64_e32 v[66:67], 0
	v_mov_b64_e32 v[68:69], 0
	v_mov_b64_e32 v[70:71], 0
	v_mov_b64_e32 v[80:81], 0
	v_mov_b64_e32 v[82:83], 0
	v_mov_b64_e32 v[84:85], 0
	v_mov_b64_e32 v[86:87], 0
	v_mov_b64_e32 v[96:97], 0
	v_mov_b64_e32 v[98:99], 0
	v_mov_b64_e32 v[100:101], 0
	v_mov_b64_e32 v[102:103], 0
	v_mov_b64_e32 v[112:113], 0
	v_mov_b64_e32 v[114:115], 0
	v_mov_b64_e32 v[116:117], 0
	v_mov_b64_e32 v[118:119], 0
	v_mov_b64_e32 v[72:73], 0
	v_mov_b64_e32 v[74:75], 0
	v_mov_b64_e32 v[76:77], 0
	v_mov_b64_e32 v[78:79], 0
	v_mov_b64_e32 v[88:89], 0
	v_mov_b64_e32 v[90:91], 0
	v_mov_b64_e32 v[92:93], 0
	v_mov_b64_e32 v[94:95], 0
	v_mov_b64_e32 v[104:105], 0
	v_mov_b64_e32 v[106:107], 0
	v_mov_b64_e32 v[108:109], 0
	v_mov_b64_e32 v[110:111], 0
	v_mov_b64_e32 v[120:121], 0
	v_mov_b64_e32 v[122:123], 0
	v_mov_b64_e32 v[124:125], 0
	v_mov_b64_e32 v[126:127], 0
	.p2align	8

.LBB0_291:
	s_ashr_i32 s41, s40, 31
	v_mov_b64_e32 v[0:1], 0x400
	s_lshl_b64 s[20:21], s[40:41], 19
	v_readlane_b32 s24, v254, 15
	v_cmp_lt_i64_e32 vcc, s[42:43], v[0:1]
	v_readlane_b32 s25, v254, 16
	s_add_u32 s42, s24, s20
	s_addc_u32 s43, s25, s21
	s_and_b64 s[20:21], vcc, exec
	s_cselect_b32 s41, s43, s47
	s_cselect_b32 s24, s42, s46
	s_ashr_i32 s1, s0, 31
	s_lshl_b64 s[20:21], s[0:1], 19
	v_readlane_b32 s44, v254, 13
	v_readlane_b32 s45, v254, 14
	s_add_u32 s44, s44, s20
	s_addc_u32 s45, s45, s21
	s_and_b64 s[20:21], vcc, exec
	s_cselect_b32 s1, s45, s29
	s_cselect_b32 s25, s44, s28
	s_add_u32 s46, s46, 0x40080
	s_addc_u32 s47, s47, 0
	s_add_u32 s58, s28, 0x100
	v_mov_b32_e32 v0, 0
	s_addc_u32 s59, s29, 0
	s_mov_b32 vcc_lo, -2
	v_mov_b32_e32 v1, v0
	v_mov_b64_e32 v[2:3], 0
	v_mov_b64_e32 v[4:5], 0
	v_mov_b64_e32 v[6:7], 0
	v_mov_b64_e32 v[8:9], 0
	v_mov_b64_e32 v[10:11], 0
	v_mov_b64_e32 v[16:17], 0
	v_mov_b64_e32 v[18:19], 0
	v_mov_b64_e32 v[24:25], 0
	v_mov_b64_e32 v[26:27], 0
	v_mov_b64_e32 v[32:33], 0
	v_mov_b64_e32 v[34:35], 0
	v_mov_b64_e32 v[40:41], 0
	v_mov_b64_e32 v[42:43], 0
	v_mov_b64_e32 v[48:49], 0
	v_mov_b64_e32 v[50:51], 0
	v_mov_b64_e32 v[12:13], 0
	v_mov_b64_e32 v[14:15], 0
	v_mov_b64_e32 v[20:21], 0
	v_mov_b64_e32 v[22:23], 0
	v_mov_b64_e32 v[28:29], 0
	v_mov_b64_e32 v[30:31], 0
	v_mov_b64_e32 v[36:37], 0
	v_mov_b64_e32 v[38:39], 0
	v_mov_b64_e32 v[44:45], 0
	v_mov_b64_e32 v[46:47], 0
	v_mov_b64_e32 v[52:53], 0
	v_mov_b64_e32 v[54:55], 0
	v_mov_b64_e32 v[56:57], 0
	v_mov_b64_e32 v[58:59], 0
	v_mov_b64_e32 v[60:61], 0
	v_mov_b64_e32 v[62:63], 0
	v_mov_b64_e32 v[64:65], 0
	v_mov_b64_e32 v[66:67], 0
	v_mov_b64_e32 v[68:69], 0
	v_mov_b64_e32 v[70:71], 0
	v_mov_b64_e32 v[76:77], 0
	v_mov_b64_e32 v[78:79], 0
	v_mov_b64_e32 v[84:85], 0
	v_mov_b64_e32 v[86:87], 0
	v_mov_b64_e32 v[88:89], 0
	v_mov_b64_e32 v[90:91], 0
	v_mov_b64_e32 v[96:97], 0
	v_mov_b64_e32 v[98:99], 0
	v_mov_b64_e32 v[104:105], 0
	v_mov_b64_e32 v[106:107], 0
	v_mov_b64_e32 v[112:113], 0
	v_mov_b64_e32 v[114:115], 0
	v_mov_b64_e32 v[72:73], 0
	v_mov_b64_e32 v[74:75], 0
	v_mov_b64_e32 v[80:81], 0
	v_mov_b64_e32 v[82:83], 0
	v_mov_b64_e32 v[92:93], 0
	v_mov_b64_e32 v[94:95], 0
	v_mov_b64_e32 v[100:101], 0
	v_mov_b64_e32 v[102:103], 0
	v_mov_b64_e32 v[108:109], 0
	v_mov_b64_e32 v[110:111], 0
	v_mov_b64_e32 v[116:117], 0
	v_mov_b64_e32 v[118:119], 0
	v_mov_b64_e32 v[120:121], 0
	v_mov_b64_e32 v[122:123], 0
	v_mov_b64_e32 v[124:125], 0
	v_mov_b64_e32 v[126:127], 0
	.p2align	8
